# v21: LDS-DMA issued before the fragment ds_reads in all four load segments of the P4, P7, P8 GEMM loops, on top of v16
# baseline (speedup 1.0000x reference)
; #define PG8_STAGE(bufoff, gbase, voff) do { _Pragma("unroll") for (int _i = 0; _i < 2; ++_i) \
;         __builtin_amdgcn_global_load_lds((const unsigned*)((const char*)(gbase) + (voff)[_i]), (LAS unsigned*)(lds + (bufoff) + ldsw + _i * 8192), 16, 0, 0); } while (0)
; #define PG8_LDA(dst, b, h) do { _Pragma("unroll") for (int m = 0; m < 4; ++m) _Pragma("unroll") for (int k = 0; k < 2; ++k) dst[m][k] = *(const LAS bf16x8*)(lds + PG8_SA(b, h) + aoff + m * 2048 + k * 1024); } while (0)
; #define PG8_LDB(dst, b, h) do { _Pragma("unroll") for (int n = 0; n < 2; ++n) _Pragma("unroll") for (int k = 0; k < 2; ++k) dst[n][k] = *(const LAS bf16x8*)(lds + PG8_SB(b, h) + boff + n * 2048 + k * 1024); } while (0)
; #define PG8_MMA(ai, bj, At, Bt) do { __builtin_amdgcn_s_setprio(1); _Pragma("unroll") for (int m = 0; m < 4; ++m) _Pragma("unroll") for (int n = 0; n < 2; ++n) _Pragma("unroll") for (int k = 0; k < 2; ++k) \
;         acc[ai][bj][m][n] = __builtin_amdgcn_mfma_f32_16x16x32_bf16(Bt[n][k], At[m][k], acc[ai][bj][m][n], 0, 0, 0); __builtin_amdgcn_s_setprio(0); } while (0)
; #define PG8_WAIT_V(n) asm volatile("s_waitcnt vmcnt(" #n ")" ::: "memory")
; #define PG8_WAIT_L(n) asm volatile("s_waitcnt lgkmcnt(" #n ")" ::: "memory")
; #define PG8_BAR __builtin_amdgcn_s_barrier()
; #define PG8_SCHED __builtin_amdgcn_sched_barrier(0)
; template <class Epi, class Sched, bool ALIGN_EPI, bool SP2>
; __device__ __forceinline__ void gemm_phase(LAS unsigned char* lds, const Gemm g, const Sched& S, const Epi& E) {
;     ...
;             PG8_LDB(B0, 0, 0); PG8_LDB(B1, 0, 1); PG8_SCHED; PG8_LDA(At, 0, 0); PG8_STAGE(PG8_SA(1, 1), a1 + hstep, voffA);
;             PG8_WAIT_V(8); PG8_WAIT_L(0); PG8_BAR; PG8_MMA(0, 0, At, B0); PG8_MMA(0, 1, At, B1); PG8_BAR; PG8_SCHED;
;             PG8_LDA(At, 0, 1); PG8_STAGE(PG8_SB(0, 0), b2, voffB); PG8_STAGE(PG8_SB(0, 1), b2 + hstep, voffB); PG8_STAGE(PG8_SA(0, 0), a2, voffA);
;             PG8_WAIT_V(8); PG8_WAIT_L(0); PG8_BAR; PG8_MMA(1, 0, At, B0); PG8_MMA(1, 1, At, B1); PG8_BAR; PG8_SCHED;
.LBB0_468:
	v_add_u32_e32 v140, s62, v187
	v_add_u32_e32 v156, s63, v187
	s_add_u32 s34, s28, 0xfffe0080
	s_addc_u32 s35, s29, -1
	s_cmp_eq_u32 s58, 4
	s_cselect_b32 s37, s21, s35
	s_cselect_b32 s36, s50, s34
	s_cselect_b32 s35, s23, s57
	s_cselect_b32 s34, s51, s56
	s_add_i32 m0, s43, 0xc000
	s_nop 0
	global_load_lds_dwordx4 v176, s[28:29]
	s_add_i32 m0, s43, 0xe000
	s_nop 0
	global_load_lds_dwordx4 v178, s[28:29]
	ds_read_b128 v[128:131], v140
	ds_read_b128 v[132:135], v140 offset:1024
	ds_read_b128 v[136:139], v140 offset:2048
	ds_read_b128 v[140:143], v140 offset:3072
	ds_read_b128 v[144:147], v156
	ds_read_b128 v[148:151], v156 offset:1024
	ds_read_b128 v[152:155], v156 offset:2048
	ds_read_b128 v[156:159], v156 offset:3072
	ds_read_b128 v[160:163], v188
	ds_read_b128 v[190:193], v188 offset:1024
	ds_read_b128 v[194:197], v188 offset:2048
	ds_read_b128 v[198:201], v188 offset:3072
	ds_read_b128 v[202:205], v188 offset:4096
	ds_read_b128 v[206:209], v188 offset:5120
	ds_read_b128 v[210:213], v188 offset:6144
	ds_read_b128 v[214:217], v188 offset:7168
	s_waitcnt vmcnt(8)
	s_waitcnt lgkmcnt(0)
	s_barrier
	s_setprio 1
	s_waitcnt lgkmcnt(0)
	v_mfma_f32_16x16x32_bf16 v[124:127], v[128:131], v[160:163], v[124:127]
	v_mfma_f32_16x16x32_bf16 v[120:123], v[136:139], v[160:163], v[120:123]
	v_mfma_f32_16x16x32_bf16 v[116:119], v[128:131], v[194:197], v[116:119]
	v_mfma_f32_16x16x32_bf16 v[112:115], v[136:139], v[194:197], v[112:115]
	v_mfma_f32_16x16x32_bf16 v[108:111], v[128:131], v[202:205], v[108:111]
	v_mfma_f32_16x16x32_bf16 v[104:107], v[136:139], v[202:205], v[104:107]
	v_mfma_f32_16x16x32_bf16 v[100:103], v[128:131], v[210:213], v[100:103]
	v_mfma_f32_16x16x32_bf16 v[96:99], v[136:139], v[210:213], v[96:99]
	v_mfma_f32_16x16x32_bf16 v[124:127], v[132:135], v[190:193], v[124:127]
	v_mfma_f32_16x16x32_bf16 v[120:123], v[140:143], v[190:193], v[120:123]
	v_mfma_f32_16x16x32_bf16 v[116:119], v[132:135], v[198:201], v[116:119]
	v_mfma_f32_16x16x32_bf16 v[112:115], v[140:143], v[198:201], v[112:115]
	v_mfma_f32_16x16x32_bf16 v[108:111], v[132:135], v[206:209], v[108:111]
	v_mfma_f32_16x16x32_bf16 v[104:107], v[140:143], v[206:209], v[104:107]
	v_mfma_f32_16x16x32_bf16 v[100:103], v[132:135], v[214:217], v[100:103]
	v_mfma_f32_16x16x32_bf16 v[96:99], v[140:143], v[214:217], v[96:99]
	s_setprio 0
	s_setprio 1
	v_mfma_f32_16x16x32_bf16 v[92:95], v[144:147], v[160:163], v[92:95]
	v_mfma_f32_16x16x32_bf16 v[88:91], v[152:155], v[160:163], v[88:91]
	v_mfma_f32_16x16x32_bf16 v[84:87], v[144:147], v[194:197], v[84:87]
	v_mfma_f32_16x16x32_bf16 v[80:83], v[152:155], v[194:197], v[80:83]
	v_mfma_f32_16x16x32_bf16 v[76:79], v[144:147], v[202:205], v[76:79]
	v_mfma_f32_16x16x32_bf16 v[72:75], v[152:155], v[202:205], v[72:75]
	v_mfma_f32_16x16x32_bf16 v[68:71], v[144:147], v[210:213], v[68:71]
	v_mfma_f32_16x16x32_bf16 v[64:67], v[152:155], v[210:213], v[64:67]
	v_mfma_f32_16x16x32_bf16 v[92:95], v[148:151], v[190:193], v[92:95]
	v_mfma_f32_16x16x32_bf16 v[88:91], v[156:159], v[190:193], v[88:91]
	v_mfma_f32_16x16x32_bf16 v[84:87], v[148:151], v[198:201], v[84:87]
	v_mfma_f32_16x16x32_bf16 v[80:83], v[156:159], v[198:201], v[80:83]
	v_mfma_f32_16x16x32_bf16 v[76:79], v[148:151], v[206:209], v[76:79]
	v_mfma_f32_16x16x32_bf16 v[72:75], v[156:159], v[206:209], v[72:75]
	v_mfma_f32_16x16x32_bf16 v[68:71], v[148:151], v[214:217], v[68:71]
	v_mfma_f32_16x16x32_bf16 v[64:67], v[156:159], v[214:217], v[64:67]
	s_setprio 0
	s_barrier
	s_add_i32 s59, s62, s42
	s_mov_b32 m0, s59
	s_nop 0
	global_load_lds_dwordx4 v166, s[34:35]
	s_add_i32 m0, s59, 0x2000
	s_add_u32 s72, s34, 0x20000
	s_addc_u32 s73, s35, 0
	s_add_i32 s59, s63, s42
	global_load_lds_dwordx4 v170, s[34:35]
	s_mov_b32 m0, s59
	s_nop 0
	global_load_lds_dwordx4 v166, s[72:73]
	s_add_i32 m0, s59, 0x2000
	s_nop 0
	global_load_lds_dwordx4 v170, s[72:73]
	s_mov_b32 m0, s43
	s_nop 0
	global_load_lds_dwordx4 v164, s[36:37]
	s_mov_b32 m0, s44
	s_nop 0
	global_load_lds_dwordx4 v168, s[36:37]
	ds_read_b128 v[160:163], v188 offset:16384
	ds_read_b128 v[190:193], v188 offset:17408
	ds_read_b128 v[194:197], v188 offset:18432
	ds_read_b128 v[198:201], v188 offset:19456
	ds_read_b128 v[202:205], v188 offset:20480
	ds_read_b128 v[206:209], v188 offset:21504
	ds_read_b128 v[210:213], v188 offset:22528
	ds_read_b128 v[214:217], v188 offset:23552
	s_waitcnt vmcnt(8)
	s_waitcnt lgkmcnt(0)
	s_barrier
	s_setprio 1
	s_waitcnt lgkmcnt(0)
	v_mfma_f32_16x16x32_bf16 v[60:63], v[128:131], v[160:163], v[60:63]
	v_mfma_f32_16x16x32_bf16 v[56:59], v[136:139], v[160:163], v[56:59]
	v_mfma_f32_16x16x32_bf16 v[52:55], v[128:131], v[194:197], v[52:55]
	v_mfma_f32_16x16x32_bf16 v[48:51], v[136:139], v[194:197], v[48:51]
	v_mfma_f32_16x16x32_bf16 v[44:47], v[128:131], v[202:205], v[44:47]
	v_mfma_f32_16x16x32_bf16 v[40:43], v[136:139], v[202:205], v[40:43]
	v_mfma_f32_16x16x32_bf16 v[36:39], v[128:131], v[210:213], v[36:39]
	v_mfma_f32_16x16x32_bf16 v[32:35], v[136:139], v[210:213], v[32:35]
	v_mfma_f32_16x16x32_bf16 v[60:63], v[132:135], v[190:193], v[60:63]
	v_mfma_f32_16x16x32_bf16 v[56:59], v[140:143], v[190:193], v[56:59]
	v_mfma_f32_16x16x32_bf16 v[52:55], v[132:135], v[198:201], v[52:55]
	v_mfma_f32_16x16x32_bf16 v[48:51], v[140:143], v[198:201], v[48:51]
	v_mfma_f32_16x16x32_bf16 v[44:47], v[132:135], v[206:209], v[44:47]
	v_mfma_f32_16x16x32_bf16 v[40:43], v[140:143], v[206:209], v[40:43]
	v_mfma_f32_16x16x32_bf16 v[36:39], v[132:135], v[214:217], v[36:39]
	v_mfma_f32_16x16x32_bf16 v[32:35], v[140:143], v[214:217], v[32:35]
	s_setprio 0
	s_setprio 1
	v_mfma_f32_16x16x32_bf16 v[28:31], v[144:147], v[160:163], v[28:31]
	v_mfma_f32_16x16x32_bf16 v[24:27], v[152:155], v[160:163], v[24:27]
	v_mfma_f32_16x16x32_bf16 v[20:23], v[144:147], v[194:197], v[20:23]
	v_mfma_f32_16x16x32_bf16 v[16:19], v[152:155], v[194:197], v[16:19]
	v_mfma_f32_16x16x32_bf16 v[12:15], v[144:147], v[202:205], v[12:15]
	v_mfma_f32_16x16x32_bf16 v[8:11], v[152:155], v[202:205], v[8:11]
	v_mfma_f32_16x16x32_bf16 v[4:7], v[144:147], v[210:213], v[4:7]
	v_mfma_f32_16x16x32_bf16 v[0:3], v[152:155], v[210:213], v[0:3]
	v_mfma_f32_16x16x32_bf16 v[28:31], v[148:151], v[190:193], v[28:31]
	v_mfma_f32_16x16x32_bf16 v[24:27], v[156:159], v[190:193], v[24:27]
	v_mfma_f32_16x16x32_bf16 v[20:23], v[148:151], v[198:201], v[20:23]
	v_mfma_f32_16x16x32_bf16 v[16:19], v[156:159], v[198:201], v[16:19]
	v_mfma_f32_16x16x32_bf16 v[12:15], v[148:151], v[206:209], v[12:15]
	v_mfma_f32_16x16x32_bf16 v[8:11], v[156:159], v[206:209], v[8:11]
	v_mfma_f32_16x16x32_bf16 v[4:7], v[148:151], v[214:217], v[4:7]
	v_mfma_f32_16x16x32_bf16 v[0:3], v[156:159], v[214:217], v[0:3]
	s_setprio 0
	s_barrier
; #define PG8_STAGE(bufoff, gbase, voff) do { _Pragma("unroll") for (int _i = 0; _i < 2; ++_i) \
;         __builtin_amdgcn_global_load_lds((const unsigned*)((const char*)(gbase) + (voff)[_i]), (LAS unsigned*)(lds + (bufoff) + ldsw + _i * 8192), 16, 0, 0); } while (0)
; #define PG8_LDA(dst, b, h) do { _Pragma("unroll") for (int m = 0; m < 4; ++m) _Pragma("unroll") for (int k = 0; k < 2; ++k) dst[m][k] = *(const LAS bf16x8*)(lds + PG8_SA(b, h) + aoff + m * 2048 + k * 1024); } while (0)
; #define PG8_LDB(dst, b, h) do { _Pragma("unroll") for (int n = 0; n < 2; ++n) _Pragma("unroll") for (int k = 0; k < 2; ++k) dst[n][k] = *(const LAS bf16x8*)(lds + PG8_SB(b, h) + boff + n * 2048 + k * 1024); } while (0)
; #define PG8_MMA(ai, bj, At, Bt) do { __builtin_amdgcn_s_setprio(1); _Pragma("unroll") for (int m = 0; m < 4; ++m) _Pragma("unroll") for (int n = 0; n < 2; ++n) _Pragma("unroll") for (int k = 0; k < 2; ++k) \
;         acc[ai][bj][m][n] = __builtin_amdgcn_mfma_f32_16x16x32_bf16(Bt[n][k], At[m][k], acc[ai][bj][m][n], 0, 0, 0); __builtin_amdgcn_s_setprio(0); } while (0)
; #define PG8_WAIT_V(n) asm volatile("s_waitcnt vmcnt(" #n ")" ::: "memory")
; #define PG8_WAIT_L(n) asm volatile("s_waitcnt lgkmcnt(" #n ")" ::: "memory")
; #define PG8_BAR __builtin_amdgcn_s_barrier()
; #define PG8_SCHED __builtin_amdgcn_sched_barrier(0)
; template <class Epi, class Sched, bool ALIGN_EPI, bool SP2>
; __device__ __forceinline__ void gemm_phase(LAS unsigned char* lds, const Gemm g, const Sched& S, const Epi& E) {
;     ...
;             PG8_LDB(B0, 1, 0); PG8_LDB(B1, 1, 1); PG8_SCHED; PG8_LDA(At, 1, 0); PG8_STAGE(PG8_SA(0, 1), a2 + hstep, voffA);
;             PG8_WAIT_V(8); PG8_WAIT_L(0); PG8_BAR; PG8_MMA(0, 0, At, B0); PG8_MMA(0, 1, At, B1); PG8_BAR; PG8_SCHED;
;             PG8_LDA(At, 1, 1); PG8_STAGE(PG8_SB(1, 0), b3, voffB); PG8_STAGE(PG8_SB(1, 1), b3 + hstep, voffB); PG8_STAGE(PG8_SA(1, 0), a3, voffA);
;             PG8_WAIT_V(8); PG8_WAIT_L(0); PG8_BAR; PG8_MMA(1, 0, At, B0); PG8_MMA(1, 1, At, B1); PG8_BAR; PG8_SCHED;
	s_add_i32 s59, 0, 0x18000
	s_add_i32 s71, 0, 0x1c000
	v_add_u32_e32 v140, s59, v187
	v_add_u32_e32 v156, s71, v187
	s_add_u32 s36, s36, 0x20000
	s_addc_u32 s37, s37, 0
	s_mov_b32 m0, s45
	s_nop 0
	global_load_lds_dwordx4 v164, s[36:37]
	s_mov_b32 m0, s46
	s_nop 0
	global_load_lds_dwordx4 v168, s[36:37]
	ds_read_b128 v[128:131], v140
	ds_read_b128 v[132:135], v140 offset:1024
	ds_read_b128 v[136:139], v140 offset:2048
	ds_read_b128 v[140:143], v140 offset:3072
	ds_read_b128 v[144:147], v156
	ds_read_b128 v[148:151], v156 offset:1024
	ds_read_b128 v[152:155], v156 offset:2048
	ds_read_b128 v[156:159], v156 offset:3072
	ds_read_b128 v[160:163], v188 offset:32768
	ds_read_b128 v[190:193], v188 offset:33792
	ds_read_b128 v[194:197], v188 offset:34816
	ds_read_b128 v[198:201], v188 offset:35840
	ds_read_b128 v[202:205], v188 offset:36864
	ds_read_b128 v[206:209], v188 offset:37888
	ds_read_b128 v[210:213], v188 offset:38912
	ds_read_b128 v[214:217], v188 offset:39936
	s_waitcnt vmcnt(8)
	s_waitcnt lgkmcnt(0)
	s_barrier
	s_setprio 1
	s_waitcnt lgkmcnt(0)
	v_mfma_f32_16x16x32_bf16 v[124:127], v[128:131], v[160:163], v[124:127]
	v_mfma_f32_16x16x32_bf16 v[120:123], v[136:139], v[160:163], v[120:123]
	v_mfma_f32_16x16x32_bf16 v[116:119], v[128:131], v[194:197], v[116:119]
	v_mfma_f32_16x16x32_bf16 v[112:115], v[136:139], v[194:197], v[112:115]
	v_mfma_f32_16x16x32_bf16 v[108:111], v[128:131], v[202:205], v[108:111]
	v_mfma_f32_16x16x32_bf16 v[104:107], v[136:139], v[202:205], v[104:107]
	v_mfma_f32_16x16x32_bf16 v[100:103], v[128:131], v[210:213], v[100:103]
	v_mfma_f32_16x16x32_bf16 v[96:99], v[136:139], v[210:213], v[96:99]
	v_mfma_f32_16x16x32_bf16 v[124:127], v[132:135], v[190:193], v[124:127]
	v_mfma_f32_16x16x32_bf16 v[120:123], v[140:143], v[190:193], v[120:123]
	v_mfma_f32_16x16x32_bf16 v[116:119], v[132:135], v[198:201], v[116:119]
	v_mfma_f32_16x16x32_bf16 v[112:115], v[140:143], v[198:201], v[112:115]
	v_mfma_f32_16x16x32_bf16 v[108:111], v[132:135], v[206:209], v[108:111]
	v_mfma_f32_16x16x32_bf16 v[104:107], v[140:143], v[206:209], v[104:107]
	v_mfma_f32_16x16x32_bf16 v[100:103], v[132:135], v[214:217], v[100:103]
	v_mfma_f32_16x16x32_bf16 v[96:99], v[140:143], v[214:217], v[96:99]
	s_setprio 0
	s_setprio 1
	v_mfma_f32_16x16x32_bf16 v[92:95], v[144:147], v[160:163], v[92:95]
	v_mfma_f32_16x16x32_bf16 v[88:91], v[152:155], v[160:163], v[88:91]
	v_mfma_f32_16x16x32_bf16 v[84:87], v[144:147], v[194:197], v[84:87]
	v_mfma_f32_16x16x32_bf16 v[80:83], v[152:155], v[194:197], v[80:83]
	v_mfma_f32_16x16x32_bf16 v[76:79], v[144:147], v[202:205], v[76:79]
	v_mfma_f32_16x16x32_bf16 v[72:75], v[152:155], v[202:205], v[72:75]
	v_mfma_f32_16x16x32_bf16 v[68:71], v[144:147], v[210:213], v[68:71]
	v_mfma_f32_16x16x32_bf16 v[64:67], v[152:155], v[210:213], v[64:67]
	v_mfma_f32_16x16x32_bf16 v[92:95], v[148:151], v[190:193], v[92:95]
	v_mfma_f32_16x16x32_bf16 v[88:91], v[156:159], v[190:193], v[88:91]
	v_mfma_f32_16x16x32_bf16 v[84:87], v[148:151], v[198:201], v[84:87]
	v_mfma_f32_16x16x32_bf16 v[80:83], v[156:159], v[198:201], v[80:83]
	v_mfma_f32_16x16x32_bf16 v[76:79], v[148:151], v[206:209], v[76:79]
	v_mfma_f32_16x16x32_bf16 v[72:75], v[156:159], v[206:209], v[72:75]
	v_mfma_f32_16x16x32_bf16 v[68:71], v[148:151], v[214:217], v[68:71]
	v_mfma_f32_16x16x32_bf16 v[64:67], v[156:159], v[214:217], v[64:67]
	s_setprio 0
	s_barrier
	s_add_u32 s100, s36, 0xfffe0080
	s_addc_u32 s101, s37, -1
	s_add_u32 s98, s34, 0x80
	s_addc_u32 s99, s35, 0
	s_add_i32 s36, s59, s42
	s_mov_b32 m0, s36
	s_nop 0
	global_load_lds_dwordx4 v166, s[98:99]
	s_add_i32 m0, s36, 0x2000
	s_add_u32 s34, s34, 0x20080
	s_addc_u32 s35, s35, 0
	s_add_i32 s36, s71, s42
	global_load_lds_dwordx4 v170, s[98:99]
	s_mov_b32 m0, s36
	s_nop 0
	global_load_lds_dwordx4 v166, s[34:35]
	s_add_i32 m0, s36, 0x2000
	s_nop 0
	global_load_lds_dwordx4 v170, s[34:35]
	s_mov_b32 m0, s54
	s_nop 0
	global_load_lds_dwordx4 v164, s[100:101]
	s_mov_b32 m0, s55
	s_nop 0
	global_load_lds_dwordx4 v168, s[100:101]
	ds_read_b128 v[160:163], v188 offset:49152
	ds_read_b128 v[190:193], v188 offset:50176
	ds_read_b128 v[194:197], v188 offset:51200
	ds_read_b128 v[198:201], v188 offset:52224
	ds_read_b128 v[202:205], v188 offset:53248
	ds_read_b128 v[206:209], v188 offset:54272
	ds_read_b128 v[210:213], v188 offset:55296
	ds_read_b128 v[214:217], v188 offset:56320
	s_waitcnt vmcnt(8)
	s_waitcnt lgkmcnt(0)
	s_barrier
	s_setprio 1
	s_waitcnt lgkmcnt(0)
	v_mfma_f32_16x16x32_bf16 v[60:63], v[128:131], v[160:163], v[60:63]
	v_mfma_f32_16x16x32_bf16 v[56:59], v[136:139], v[160:163], v[56:59]
	v_mfma_f32_16x16x32_bf16 v[52:55], v[128:131], v[194:197], v[52:55]
	v_mfma_f32_16x16x32_bf16 v[48:51], v[136:139], v[194:197], v[48:51]
	v_mfma_f32_16x16x32_bf16 v[44:47], v[128:131], v[202:205], v[44:47]
	v_mfma_f32_16x16x32_bf16 v[40:43], v[136:139], v[202:205], v[40:43]
	v_mfma_f32_16x16x32_bf16 v[36:39], v[128:131], v[210:213], v[36:39]
	v_mfma_f32_16x16x32_bf16 v[32:35], v[136:139], v[210:213], v[32:35]
	v_mfma_f32_16x16x32_bf16 v[60:63], v[132:135], v[190:193], v[60:63]
	v_mfma_f32_16x16x32_bf16 v[56:59], v[140:143], v[190:193], v[56:59]
	v_mfma_f32_16x16x32_bf16 v[52:55], v[132:135], v[198:201], v[52:55]
	v_mfma_f32_16x16x32_bf16 v[48:51], v[140:143], v[198:201], v[48:51]
	v_mfma_f32_16x16x32_bf16 v[44:47], v[132:135], v[206:209], v[44:47]
	v_mfma_f32_16x16x32_bf16 v[40:43], v[140:143], v[206:209], v[40:43]
	v_mfma_f32_16x16x32_bf16 v[36:39], v[132:135], v[214:217], v[36:39]
	v_mfma_f32_16x16x32_bf16 v[32:35], v[140:143], v[214:217], v[32:35]
	s_setprio 0
	s_setprio 1
	v_mfma_f32_16x16x32_bf16 v[28:31], v[144:147], v[160:163], v[28:31]
	v_mfma_f32_16x16x32_bf16 v[24:27], v[152:155], v[160:163], v[24:27]
	v_mfma_f32_16x16x32_bf16 v[20:23], v[144:147], v[194:197], v[20:23]
	v_mfma_f32_16x16x32_bf16 v[16:19], v[152:155], v[194:197], v[16:19]
	v_mfma_f32_16x16x32_bf16 v[12:15], v[144:147], v[202:205], v[12:15]
	v_mfma_f32_16x16x32_bf16 v[8:11], v[152:155], v[202:205], v[8:11]
	v_mfma_f32_16x16x32_bf16 v[4:7], v[144:147], v[210:213], v[4:7]
	v_mfma_f32_16x16x32_bf16 v[0:3], v[152:155], v[210:213], v[0:3]
	v_mfma_f32_16x16x32_bf16 v[28:31], v[148:151], v[190:193], v[28:31]
	v_mfma_f32_16x16x32_bf16 v[24:27], v[156:159], v[190:193], v[24:27]
	v_mfma_f32_16x16x32_bf16 v[20:23], v[148:151], v[198:201], v[20:23]
	v_mfma_f32_16x16x32_bf16 v[16:19], v[156:159], v[198:201], v[16:19]
	v_mfma_f32_16x16x32_bf16 v[12:15], v[148:151], v[206:209], v[12:15]
	v_mfma_f32_16x16x32_bf16 v[8:11], v[156:159], v[206:209], v[8:11]
	v_mfma_f32_16x16x32_bf16 v[4:7], v[148:151], v[214:217], v[4:7]
	v_mfma_f32_16x16x32_bf16 v[0:3], v[156:159], v[214:217], v[0:3]
	s_setprio 0
	s_barrier
	s_add_i32 s58, s58, 2
	s_add_u32 s28, s28, 0x100
	s_addc_u32 s29, s29, 0
	s_add_u32 s56, s56, 0x100
	s_addc_u32 s57, s57, 0
	s_cmp_gt_u32 s58, 5
	s_cbranch_scc0 .LBB0_468
	s_and_b64 vcc, exec, s[18:19]
	s_cbranch_vccz .LBB0_471
	s_barrier

; #define PG8_STAGE(bufoff, gbase, voff) do { _Pragma("unroll") for (int _i = 0; _i < 2; ++_i) \
;         __builtin_amdgcn_global_load_lds((const unsigned*)((const char*)(gbase) + (voff)[_i]), (LAS unsigned*)(lds + (bufoff) + ldsw + _i * 8192), 16, 0, 0); } while (0)
; #define PG8_LDA(dst, b, h) do { _Pragma("unroll") for (int m = 0; m < 4; ++m) _Pragma("unroll") for (int k = 0; k < 2; ++k) dst[m][k] = *(const LAS bf16x8*)(lds + PG8_SA(b, h) + aoff + m * 2048 + k * 1024); } while (0)
; #define PG8_LDB(dst, b, h) do { _Pragma("unroll") for (int n = 0; n < 2; ++n) _Pragma("unroll") for (int k = 0; k < 2; ++k) dst[n][k] = *(const LAS bf16x8*)(lds + PG8_SB(b, h) + boff + n * 2048 + k * 1024); } while (0)
; #define PG8_MMA(ai, bj, At, Bt) do { __builtin_amdgcn_s_setprio(1); _Pragma("unroll") for (int m = 0; m < 4; ++m) _Pragma("unroll") for (int n = 0; n < 2; ++n) _Pragma("unroll") for (int k = 0; k < 2; ++k) \
;         acc[ai][bj][m][n] = __builtin_amdgcn_mfma_f32_16x16x32_bf16(Bt[n][k], At[m][k], acc[ai][bj][m][n], 0, 0, 0); __builtin_amdgcn_s_setprio(0); } while (0)
; #define PG8_WAIT_V(n) asm volatile("s_waitcnt vmcnt(" #n ")" ::: "memory")
; #define PG8_WAIT_L(n) asm volatile("s_waitcnt lgkmcnt(" #n ")" ::: "memory")
; #define PG8_BAR __builtin_amdgcn_s_barrier()
; #define PG8_SCHED __builtin_amdgcn_sched_barrier(0)
; template <class Epi, class Sched, bool ALIGN_EPI, bool SP2>
; __device__ __forceinline__ void gemm_phase(LAS unsigned char* lds, const Gemm g, const Sched& S, const Epi& E) {
;     ...
;             const char* a1 = cA + (size_t)(t + 1) * kstep;
;             const char* a2 = last ? nA : cA + (size_t)(t + 2) * kstep; const char* b2 = last ? nB : cB + (size_t)(t + 2) * kstep;
;             const char* a3 = a2 + kstep; const char* b3 = b2 + kstep;
;             if constexpr (SP2) {
;             PG8_LDB(B0, 0, 0); PG8_LDB(B1, 0, 1); PG8_SCHED; PG8_LDA(At, 0, 0); PG8_STAGE(PG8_SA(1, 1), a1 + hstep, voffA);
;             PG8_WAIT_V(8); PG8_WAIT_L(0); PG8_BAR; PG8_MMA(0, 0, At, B0); PG8_MMA(0, 1, At, B1); PG8_BAR; PG8_SCHED;
;             PG8_LDA(At, 0, 1); PG8_STAGE(PG8_SB(0, 0), b2, voffB); PG8_STAGE(PG8_SB(0, 1), b2 + hstep, voffB); PG8_STAGE(PG8_SA(0, 0), a2, voffA);
;             PG8_WAIT_V(8); PG8_WAIT_L(0); PG8_BAR; PG8_MMA(1, 0, At, B0); PG8_MMA(1, 1, At, B1); PG8_BAR; PG8_SCHED;
.LBB0_683:
	s_add_u32 s26, s24, 0xfffc0080
	s_addc_u32 s27, s25, -1
	s_cmp_eq_u32 s52, 12
	s_cselect_b32 s29, s15, s27
	s_cselect_b32 s28, s48, s26
	s_cselect_b32 s27, s17, s51
	s_cselect_b32 s26, s49, s50
	s_add_i32 m0, s23, 0xc000
	s_nop 0
	global_load_lds_dwordx4 v136, s[24:25]
	s_add_i32 m0, s23, 0xe000
	s_nop 0
	global_load_lds_dwordx4 v138, s[24:25]
	ds_read_b128 v[150:153], v147
	ds_read_b128 v[154:157], v147 offset:1024
	ds_read_b128 v[158:161], v147 offset:2048
	ds_read_b128 v[162:165], v147 offset:3072
	ds_read_b128 v[166:169], v148
	ds_read_b128 v[170:173], v148 offset:1024
	ds_read_b128 v[176:179], v148 offset:2048
	ds_read_b128 v[180:183], v148 offset:3072
	ds_read_b128 v[184:187], v149
	ds_read_b128 v[188:191], v149 offset:1024
	ds_read_b128 v[192:195], v149 offset:2048
	ds_read_b128 v[196:199], v149 offset:3072
	ds_read_b128 v[200:203], v149 offset:4096
	ds_read_b128 v[204:207], v149 offset:5120
	ds_read_b128 v[208:211], v149 offset:6144
	ds_read_b128 v[212:215], v149 offset:7168
	s_waitcnt vmcnt(8)
	s_waitcnt lgkmcnt(0)
	s_barrier
	s_setprio 1
	s_waitcnt lgkmcnt(0)
	v_mfma_f32_16x16x32_bf16 v[124:127], v[150:153], v[184:187], v[124:127]
	v_mfma_f32_16x16x32_bf16 v[120:123], v[158:161], v[184:187], v[120:123]
	v_mfma_f32_16x16x32_bf16 v[108:111], v[150:153], v[192:195], v[108:111]
	v_mfma_f32_16x16x32_bf16 v[104:107], v[158:161], v[192:195], v[104:107]
	v_mfma_f32_16x16x32_bf16 v[92:95], v[150:153], v[200:203], v[92:95]
	v_mfma_f32_16x16x32_bf16 v[88:91], v[158:161], v[200:203], v[88:91]
	v_mfma_f32_16x16x32_bf16 v[76:79], v[150:153], v[208:211], v[76:79]
	v_mfma_f32_16x16x32_bf16 v[72:75], v[158:161], v[208:211], v[72:75]
	v_mfma_f32_16x16x32_bf16 v[124:127], v[154:157], v[188:191], v[124:127]
	v_mfma_f32_16x16x32_bf16 v[120:123], v[162:165], v[188:191], v[120:123]
	v_mfma_f32_16x16x32_bf16 v[108:111], v[154:157], v[196:199], v[108:111]
	v_mfma_f32_16x16x32_bf16 v[104:107], v[162:165], v[196:199], v[104:107]
	v_mfma_f32_16x16x32_bf16 v[92:95], v[154:157], v[204:207], v[92:95]
	v_mfma_f32_16x16x32_bf16 v[88:91], v[162:165], v[204:207], v[88:91]
	v_mfma_f32_16x16x32_bf16 v[76:79], v[154:157], v[212:215], v[76:79]
	v_mfma_f32_16x16x32_bf16 v[72:75], v[162:165], v[212:215], v[72:75]
	s_setprio 0
	s_setprio 1
	v_mfma_f32_16x16x32_bf16 v[116:119], v[166:169], v[184:187], v[116:119]
	v_mfma_f32_16x16x32_bf16 v[112:115], v[176:179], v[184:187], v[112:115]
	v_mfma_f32_16x16x32_bf16 v[100:103], v[166:169], v[192:195], v[100:103]
	v_mfma_f32_16x16x32_bf16 v[96:99], v[176:179], v[192:195], v[96:99]
	v_mfma_f32_16x16x32_bf16 v[84:87], v[166:169], v[200:203], v[84:87]
	v_mfma_f32_16x16x32_bf16 v[80:83], v[176:179], v[200:203], v[80:83]
	v_mfma_f32_16x16x32_bf16 v[68:71], v[166:169], v[208:211], v[68:71]
	v_mfma_f32_16x16x32_bf16 v[64:67], v[176:179], v[208:211], v[64:67]
	v_mfma_f32_16x16x32_bf16 v[116:119], v[170:173], v[188:191], v[116:119]
	v_mfma_f32_16x16x32_bf16 v[112:115], v[180:183], v[188:191], v[112:115]
	v_mfma_f32_16x16x32_bf16 v[100:103], v[170:173], v[196:199], v[100:103]
	v_mfma_f32_16x16x32_bf16 v[96:99], v[180:183], v[196:199], v[96:99]
	v_mfma_f32_16x16x32_bf16 v[84:87], v[170:173], v[204:207], v[84:87]
	v_mfma_f32_16x16x32_bf16 v[80:83], v[180:183], v[204:207], v[80:83]
	v_mfma_f32_16x16x32_bf16 v[68:71], v[170:173], v[212:215], v[68:71]
	v_mfma_f32_16x16x32_bf16 v[64:67], v[180:183], v[212:215], v[64:67]
	s_setprio 0
	s_barrier
	s_add_i32 s53, s44, s30
	s_mov_b32 m0, s53
	s_nop 0
	global_load_lds_dwordx4 v132, s[26:27]
	s_add_i32 m0, s53, 0x2000
	s_add_u32 s54, s26, 0x40000
	s_addc_u32 s55, s27, 0
	s_add_i32 s53, s45, s30
	global_load_lds_dwordx4 v128, s[26:27]
	s_mov_b32 m0, s53
	s_nop 0
	global_load_lds_dwordx4 v132, s[54:55]
	s_add_i32 m0, s53, 0x2000
	s_nop 0
	global_load_lds_dwordx4 v128, s[54:55]
	s_mov_b32 m0, s23
	s_nop 0
	global_load_lds_dwordx4 v134, s[28:29]
	s_mov_b32 m0, s34
	s_nop 0
	global_load_lds_dwordx4 v130, s[28:29]
	ds_read_b128 v[184:187], v149 offset:16384
	ds_read_b128 v[188:191], v149 offset:17408
	ds_read_b128 v[192:195], v149 offset:18432
	ds_read_b128 v[196:199], v149 offset:19456
	ds_read_b128 v[200:203], v149 offset:20480
	ds_read_b128 v[204:207], v149 offset:21504
	ds_read_b128 v[208:211], v149 offset:22528
	ds_read_b128 v[212:215], v149 offset:23552
	s_waitcnt vmcnt(8)
	s_waitcnt lgkmcnt(0)
	s_barrier
	s_setprio 1
	s_waitcnt lgkmcnt(0)
	v_mfma_f32_16x16x32_bf16 v[60:63], v[150:153], v[184:187], v[60:63]
	v_mfma_f32_16x16x32_bf16 v[56:59], v[158:161], v[184:187], v[56:59]
	v_mfma_f32_16x16x32_bf16 v[44:47], v[150:153], v[192:195], v[44:47]
	v_mfma_f32_16x16x32_bf16 v[40:43], v[158:161], v[192:195], v[40:43]
	v_mfma_f32_16x16x32_bf16 v[28:31], v[150:153], v[200:203], v[28:31]
	v_mfma_f32_16x16x32_bf16 v[24:27], v[158:161], v[200:203], v[24:27]
	v_mfma_f32_16x16x32_bf16 v[12:15], v[150:153], v[208:211], v[12:15]
	v_mfma_f32_16x16x32_bf16 v[8:11], v[158:161], v[208:211], v[8:11]
	v_mfma_f32_16x16x32_bf16 v[60:63], v[154:157], v[188:191], v[60:63]
	v_mfma_f32_16x16x32_bf16 v[56:59], v[162:165], v[188:191], v[56:59]
	v_mfma_f32_16x16x32_bf16 v[44:47], v[154:157], v[196:199], v[44:47]
	v_mfma_f32_16x16x32_bf16 v[40:43], v[162:165], v[196:199], v[40:43]
	v_mfma_f32_16x16x32_bf16 v[28:31], v[154:157], v[204:207], v[28:31]
	v_mfma_f32_16x16x32_bf16 v[24:27], v[162:165], v[204:207], v[24:27]
	v_mfma_f32_16x16x32_bf16 v[12:15], v[154:157], v[212:215], v[12:15]
	v_mfma_f32_16x16x32_bf16 v[8:11], v[162:165], v[212:215], v[8:11]
	s_setprio 0
	s_setprio 1
	v_mfma_f32_16x16x32_bf16 v[52:55], v[166:169], v[184:187], v[52:55]
	v_mfma_f32_16x16x32_bf16 v[48:51], v[176:179], v[184:187], v[48:51]
	v_mfma_f32_16x16x32_bf16 v[36:39], v[166:169], v[192:195], v[36:39]
	v_mfma_f32_16x16x32_bf16 v[32:35], v[176:179], v[192:195], v[32:35]
	v_mfma_f32_16x16x32_bf16 v[20:23], v[166:169], v[200:203], v[20:23]
	v_mfma_f32_16x16x32_bf16 v[16:19], v[176:179], v[200:203], v[16:19]
	v_mfma_f32_16x16x32_bf16 v[4:7], v[166:169], v[208:211], v[4:7]
	v_mfma_f32_16x16x32_bf16 v[0:3], v[176:179], v[208:211], v[0:3]
	v_mfma_f32_16x16x32_bf16 v[52:55], v[170:173], v[188:191], v[52:55]
	v_mfma_f32_16x16x32_bf16 v[48:51], v[180:183], v[188:191], v[48:51]
	v_mfma_f32_16x16x32_bf16 v[36:39], v[170:173], v[196:199], v[36:39]
	v_mfma_f32_16x16x32_bf16 v[32:35], v[180:183], v[196:199], v[32:35]
	v_mfma_f32_16x16x32_bf16 v[20:23], v[170:173], v[204:207], v[20:23]
	v_mfma_f32_16x16x32_bf16 v[16:19], v[180:183], v[204:207], v[16:19]
	v_mfma_f32_16x16x32_bf16 v[4:7], v[170:173], v[212:215], v[4:7]
	v_mfma_f32_16x16x32_bf16 v[0:3], v[180:183], v[212:215], v[0:3]
	s_setprio 0
	s_barrier
; #define PG8_STAGE(bufoff, gbase, voff) do { _Pragma("unroll") for (int _i = 0; _i < 2; ++_i) \
;         __builtin_amdgcn_global_load_lds((const unsigned*)((const char*)(gbase) + (voff)[_i]), (LAS unsigned*)(lds + (bufoff) + ldsw + _i * 8192), 16, 0, 0); } while (0)
; #define PG8_LDA(dst, b, h) do { _Pragma("unroll") for (int m = 0; m < 4; ++m) _Pragma("unroll") for (int k = 0; k < 2; ++k) dst[m][k] = *(const LAS bf16x8*)(lds + PG8_SA(b, h) + aoff + m * 2048 + k * 1024); } while (0)
; #define PG8_LDB(dst, b, h) do { _Pragma("unroll") for (int n = 0; n < 2; ++n) _Pragma("unroll") for (int k = 0; k < 2; ++k) dst[n][k] = *(const LAS bf16x8*)(lds + PG8_SB(b, h) + boff + n * 2048 + k * 1024); } while (0)
; #define PG8_MMA(ai, bj, At, Bt) do { __builtin_amdgcn_s_setprio(1); _Pragma("unroll") for (int m = 0; m < 4; ++m) _Pragma("unroll") for (int n = 0; n < 2; ++n) _Pragma("unroll") for (int k = 0; k < 2; ++k) \
;         acc[ai][bj][m][n] = __builtin_amdgcn_mfma_f32_16x16x32_bf16(Bt[n][k], At[m][k], acc[ai][bj][m][n], 0, 0, 0); __builtin_amdgcn_s_setprio(0); } while (0)
; #define PG8_WAIT_V(n) asm volatile("s_waitcnt vmcnt(" #n ")" ::: "memory")
; #define PG8_WAIT_L(n) asm volatile("s_waitcnt lgkmcnt(" #n ")" ::: "memory")
; #define PG8_BAR __builtin_amdgcn_s_barrier()
; #define PG8_SCHED __builtin_amdgcn_sched_barrier(0)
; template <class Epi, class Sched, bool ALIGN_EPI, bool SP2>
; __device__ __forceinline__ void gemm_phase(LAS unsigned char* lds, const Gemm g, const Sched& S, const Epi& E) {
;     ...
;             PG8_LDB(B0, 1, 0); PG8_LDB(B1, 1, 1); PG8_SCHED; PG8_LDA(At, 1, 0); PG8_STAGE(PG8_SA(0, 1), a2 + hstep, voffA);
;             PG8_WAIT_V(8); PG8_WAIT_L(0); PG8_BAR; PG8_MMA(0, 0, At, B0); PG8_MMA(0, 1, At, B1); PG8_BAR; PG8_SCHED;
;             PG8_LDA(At, 1, 1); PG8_STAGE(PG8_SB(1, 0), b3, voffB); PG8_STAGE(PG8_SB(1, 1), b3 + hstep, voffB); PG8_STAGE(PG8_SA(1, 0), a3, voffA);
;             PG8_WAIT_V(8); PG8_WAIT_L(0); PG8_BAR; PG8_MMA(1, 0, At, B0); PG8_MMA(1, 1, At, B1); PG8_BAR; PG8_SCHED;
	s_add_i32 s53, 0, 0x18000
	s_add_i32 s54, 0, 0x1c000
	v_add_u32_e32 v162, s53, v145
	v_add_u32_e32 v174, s54, v145
	s_add_u32 s28, s28, 0x40000
	s_addc_u32 s29, s29, 0
	s_mov_b32 m0, s35
	s_nop 0
	global_load_lds_dwordx4 v134, s[28:29]
	s_mov_b32 m0, s36
	s_nop 0
	global_load_lds_dwordx4 v130, s[28:29]
	ds_read_b128 v[150:153], v162
	ds_read_b128 v[154:157], v162 offset:1024
	ds_read_b128 v[158:161], v162 offset:2048
	ds_read_b128 v[162:165], v162 offset:3072
	ds_read_b128 v[166:169], v174
	ds_read_b128 v[170:173], v174 offset:1024
	ds_read_b128 v[176:179], v174 offset:2048
	ds_read_b128 v[180:183], v174 offset:3072
	ds_read_b128 v[184:187], v149 offset:32768
	ds_read_b128 v[188:191], v149 offset:33792
	ds_read_b128 v[192:195], v149 offset:34816
	ds_read_b128 v[196:199], v149 offset:35840
	ds_read_b128 v[200:203], v149 offset:36864
	ds_read_b128 v[204:207], v149 offset:37888
	ds_read_b128 v[208:211], v149 offset:38912
	ds_read_b128 v[212:215], v149 offset:39936
	s_waitcnt vmcnt(8)
	s_waitcnt lgkmcnt(0)
	s_barrier
	s_setprio 1
	s_waitcnt lgkmcnt(0)
	v_mfma_f32_16x16x32_bf16 v[124:127], v[150:153], v[184:187], v[124:127]
	v_mfma_f32_16x16x32_bf16 v[120:123], v[158:161], v[184:187], v[120:123]
	v_mfma_f32_16x16x32_bf16 v[108:111], v[150:153], v[192:195], v[108:111]
	v_mfma_f32_16x16x32_bf16 v[104:107], v[158:161], v[192:195], v[104:107]
	v_mfma_f32_16x16x32_bf16 v[92:95], v[150:153], v[200:203], v[92:95]
	v_mfma_f32_16x16x32_bf16 v[88:91], v[158:161], v[200:203], v[88:91]
	v_mfma_f32_16x16x32_bf16 v[76:79], v[150:153], v[208:211], v[76:79]
	v_mfma_f32_16x16x32_bf16 v[72:75], v[158:161], v[208:211], v[72:75]
	v_mfma_f32_16x16x32_bf16 v[124:127], v[154:157], v[188:191], v[124:127]
	v_mfma_f32_16x16x32_bf16 v[120:123], v[162:165], v[188:191], v[120:123]
	v_mfma_f32_16x16x32_bf16 v[108:111], v[154:157], v[196:199], v[108:111]
	v_mfma_f32_16x16x32_bf16 v[104:107], v[162:165], v[196:199], v[104:107]
	v_mfma_f32_16x16x32_bf16 v[92:95], v[154:157], v[204:207], v[92:95]
	v_mfma_f32_16x16x32_bf16 v[88:91], v[162:165], v[204:207], v[88:91]
	v_mfma_f32_16x16x32_bf16 v[76:79], v[154:157], v[212:215], v[76:79]
	v_mfma_f32_16x16x32_bf16 v[72:75], v[162:165], v[212:215], v[72:75]
	s_setprio 0
	s_setprio 1
	v_mfma_f32_16x16x32_bf16 v[116:119], v[166:169], v[184:187], v[116:119]
	v_mfma_f32_16x16x32_bf16 v[112:115], v[176:179], v[184:187], v[112:115]
	v_mfma_f32_16x16x32_bf16 v[100:103], v[166:169], v[192:195], v[100:103]
	v_mfma_f32_16x16x32_bf16 v[96:99], v[176:179], v[192:195], v[96:99]
	v_mfma_f32_16x16x32_bf16 v[84:87], v[166:169], v[200:203], v[84:87]
	v_mfma_f32_16x16x32_bf16 v[80:83], v[176:179], v[200:203], v[80:83]
	v_mfma_f32_16x16x32_bf16 v[68:71], v[166:169], v[208:211], v[68:71]
	v_mfma_f32_16x16x32_bf16 v[64:67], v[176:179], v[208:211], v[64:67]
	v_mfma_f32_16x16x32_bf16 v[116:119], v[170:173], v[188:191], v[116:119]
	v_mfma_f32_16x16x32_bf16 v[112:115], v[180:183], v[188:191], v[112:115]
	v_mfma_f32_16x16x32_bf16 v[100:103], v[170:173], v[196:199], v[100:103]
	v_mfma_f32_16x16x32_bf16 v[96:99], v[180:183], v[196:199], v[96:99]
	v_mfma_f32_16x16x32_bf16 v[84:87], v[170:173], v[204:207], v[84:87]
	v_mfma_f32_16x16x32_bf16 v[80:83], v[180:183], v[204:207], v[80:83]
	v_mfma_f32_16x16x32_bf16 v[68:71], v[170:173], v[212:215], v[68:71]
	v_mfma_f32_16x16x32_bf16 v[64:67], v[180:183], v[212:215], v[64:67]
	s_setprio 0
	s_barrier
	s_add_u32 s100, s28, 0xfffc0080
	s_addc_u32 s101, s29, -1
	s_add_u32 s98, s26, 0x80
	s_addc_u32 s99, s27, 0
	s_add_i32 s28, s53, s30
	s_mov_b32 m0, s28
	s_nop 0
	global_load_lds_dwordx4 v132, s[98:99]
	s_add_i32 m0, s28, 0x2000
	s_add_u32 s26, s26, 0x40080
	s_addc_u32 s27, s27, 0
	s_add_i32 s28, s54, s30
	global_load_lds_dwordx4 v128, s[98:99]
	s_mov_b32 m0, s28
	s_nop 0
	global_load_lds_dwordx4 v132, s[26:27]
	s_add_i32 m0, s28, 0x2000
	s_nop 0
	global_load_lds_dwordx4 v128, s[26:27]
	s_mov_b32 m0, s38
	s_nop 0
	global_load_lds_dwordx4 v134, s[100:101]
	s_mov_b32 m0, s39
	s_nop 0
	global_load_lds_dwordx4 v130, s[100:101]
	ds_read_b128 v[184:187], v149 offset:49152
	ds_read_b128 v[188:191], v149 offset:50176
	ds_read_b128 v[192:195], v149 offset:51200
	ds_read_b128 v[196:199], v149 offset:52224
	ds_read_b128 v[200:203], v149 offset:53248
	ds_read_b128 v[204:207], v149 offset:54272
	ds_read_b128 v[208:211], v149 offset:55296
	ds_read_b128 v[212:215], v149 offset:56320
	s_waitcnt vmcnt(8)
	s_waitcnt lgkmcnt(0)
	s_barrier
	s_setprio 1
	s_waitcnt lgkmcnt(0)
	v_mfma_f32_16x16x32_bf16 v[60:63], v[150:153], v[184:187], v[60:63]
	v_mfma_f32_16x16x32_bf16 v[56:59], v[158:161], v[184:187], v[56:59]
	v_mfma_f32_16x16x32_bf16 v[44:47], v[150:153], v[192:195], v[44:47]
	v_mfma_f32_16x16x32_bf16 v[40:43], v[158:161], v[192:195], v[40:43]
	v_mfma_f32_16x16x32_bf16 v[28:31], v[150:153], v[200:203], v[28:31]
	v_mfma_f32_16x16x32_bf16 v[24:27], v[158:161], v[200:203], v[24:27]
	v_mfma_f32_16x16x32_bf16 v[12:15], v[150:153], v[208:211], v[12:15]
	v_mfma_f32_16x16x32_bf16 v[8:11], v[158:161], v[208:211], v[8:11]
	v_mfma_f32_16x16x32_bf16 v[60:63], v[154:157], v[188:191], v[60:63]
	v_mfma_f32_16x16x32_bf16 v[56:59], v[162:165], v[188:191], v[56:59]
	v_mfma_f32_16x16x32_bf16 v[44:47], v[154:157], v[196:199], v[44:47]
	v_mfma_f32_16x16x32_bf16 v[40:43], v[162:165], v[196:199], v[40:43]
	v_mfma_f32_16x16x32_bf16 v[28:31], v[154:157], v[204:207], v[28:31]
	v_mfma_f32_16x16x32_bf16 v[24:27], v[162:165], v[204:207], v[24:27]
	v_mfma_f32_16x16x32_bf16 v[12:15], v[154:157], v[212:215], v[12:15]
	v_mfma_f32_16x16x32_bf16 v[8:11], v[162:165], v[212:215], v[8:11]
	s_setprio 0
	s_setprio 1
	v_mfma_f32_16x16x32_bf16 v[52:55], v[166:169], v[184:187], v[52:55]
	v_mfma_f32_16x16x32_bf16 v[48:51], v[176:179], v[184:187], v[48:51]
	v_mfma_f32_16x16x32_bf16 v[36:39], v[166:169], v[192:195], v[36:39]
	v_mfma_f32_16x16x32_bf16 v[32:35], v[176:179], v[192:195], v[32:35]
	v_mfma_f32_16x16x32_bf16 v[20:23], v[166:169], v[200:203], v[20:23]
	v_mfma_f32_16x16x32_bf16 v[16:19], v[176:179], v[200:203], v[16:19]
	v_mfma_f32_16x16x32_bf16 v[4:7], v[166:169], v[208:211], v[4:7]
	v_mfma_f32_16x16x32_bf16 v[0:3], v[176:179], v[208:211], v[0:3]
	v_mfma_f32_16x16x32_bf16 v[52:55], v[170:173], v[188:191], v[52:55]
	v_mfma_f32_16x16x32_bf16 v[48:51], v[180:183], v[188:191], v[48:51]
	v_mfma_f32_16x16x32_bf16 v[36:39], v[170:173], v[196:199], v[36:39]
	v_mfma_f32_16x16x32_bf16 v[32:35], v[180:183], v[196:199], v[32:35]
	v_mfma_f32_16x16x32_bf16 v[20:23], v[170:173], v[204:207], v[20:23]
	v_mfma_f32_16x16x32_bf16 v[16:19], v[180:183], v[204:207], v[16:19]
	v_mfma_f32_16x16x32_bf16 v[4:7], v[170:173], v[212:215], v[4:7]
	v_mfma_f32_16x16x32_bf16 v[0:3], v[180:183], v[212:215], v[0:3]
	s_setprio 0
	s_barrier
	s_add_i32 s52, s52, 2
	s_add_u32 s24, s24, 0x100
	s_addc_u32 s25, s25, 0
	s_add_u32 s50, s50, 0x100
	s_addc_u32 s51, s51, 0
	s_cmp_gt_u32 s52, 13
	s_cbranch_scc0 .LBB0_683
	s_and_b64 vcc, exec, s[12:13]
	s_cbranch_vccz .LBB0_686
	s_barrier

; #define PG8_STAGE(bufoff, gbase, voff) do { _Pragma("unroll") for (int _i = 0; _i < 2; ++_i) \
;         __builtin_amdgcn_global_load_lds((const unsigned*)((const char*)(gbase) + (voff)[_i]), (LAS unsigned*)(lds + (bufoff) + ldsw + _i * 8192), 16, 0, 0); } while (0)
; #define PG8_LDA(dst, b, h) do { _Pragma("unroll") for (int m = 0; m < 4; ++m) _Pragma("unroll") for (int k = 0; k < 2; ++k) dst[m][k] = *(const LAS bf16x8*)(lds + PG8_SA(b, h) + aoff + m * 2048 + k * 1024); } while (0)
; #define PG8_LDB(dst, b, h) do { _Pragma("unroll") for (int n = 0; n < 2; ++n) _Pragma("unroll") for (int k = 0; k < 2; ++k) dst[n][k] = *(const LAS bf16x8*)(lds + PG8_SB(b, h) + boff + n * 2048 + k * 1024); } while (0)
; #define PG8_MMA(ai, bj, At, Bt) do { __builtin_amdgcn_s_setprio(1); _Pragma("unroll") for (int m = 0; m < 4; ++m) _Pragma("unroll") for (int n = 0; n < 2; ++n) _Pragma("unroll") for (int k = 0; k < 2; ++k) \
;         acc[ai][bj][m][n] = __builtin_amdgcn_mfma_f32_16x16x32_bf16(Bt[n][k], At[m][k], acc[ai][bj][m][n], 0, 0, 0); __builtin_amdgcn_s_setprio(0); } while (0)
; #define PG8_WAIT_V(n) asm volatile("s_waitcnt vmcnt(" #n ")" ::: "memory")
; #define PG8_WAIT_L(n) asm volatile("s_waitcnt lgkmcnt(" #n ")" ::: "memory")
; #define PG8_BAR __builtin_amdgcn_s_barrier()
; #define PG8_SCHED __builtin_amdgcn_sched_barrier(0)
; template <class Epi, class Sched, bool ALIGN_EPI, bool SP2>
; __device__ __forceinline__ void gemm_phase(LAS unsigned char* lds, const Gemm g, const Sched& S, const Epi& E) {
;     ...
;             const char* a1 = cA + (size_t)(t + 1) * kstep;
;             const char* a2 = last ? nA : cA + (size_t)(t + 2) * kstep; const char* b2 = last ? nB : cB + (size_t)(t + 2) * kstep;
;             const char* a3 = a2 + kstep; const char* b3 = b2 + kstep;
;             if constexpr (SP2) {
;             PG8_LDB(B0, 0, 0); PG8_LDB(B1, 0, 1); PG8_SCHED; PG8_LDA(At, 0, 0); PG8_STAGE(PG8_SA(1, 1), a1 + hstep, voffA);
;             PG8_WAIT_V(8); PG8_WAIT_L(0); PG8_BAR; PG8_MMA(0, 0, At, B0); PG8_MMA(0, 1, At, B1); PG8_BAR; PG8_SCHED;
;             PG8_LDA(At, 0, 1); PG8_STAGE(PG8_SB(0, 0), b2, voffB); PG8_STAGE(PG8_SB(0, 1), b2 + hstep, voffB); PG8_STAGE(PG8_SA(0, 0), a2, voffA);
;             PG8_WAIT_V(8); PG8_WAIT_L(0); PG8_BAR; PG8_MMA(1, 0, At, B0); PG8_MMA(1, 1, At, B1); PG8_BAR; PG8_SCHED;
.LBB0_766:
	s_add_u32 s26, s24, 0x100
	s_addc_u32 s27, s25, 0
	s_cmp_eq_u32 s56, 40
	s_cselect_b32 s31, s5, s27
	s_cselect_b32 s30, s4, s26
	s_cselect_b32 s29, s23, s55
	s_cselect_b32 s28, s22, s54
	s_add_i32 m0, s37, 0xc000
	s_nop 0
	global_load_lds_dwordx4 v152, s[24:25]
	s_add_i32 m0, s37, 0xe000
	s_nop 0
	global_load_lds_dwordx4 v154, s[24:25]
	ds_read_b128 v[120:123], v169
	ds_read_b128 v[124:127], v169 offset:1024
	ds_read_b128 v[136:139], v169 offset:2048
	ds_read_b128 v[140:143], v169 offset:3072
	ds_read_b128 v[160:163], v170
	ds_read_b128 v[172:175], v170 offset:1024
	ds_read_b128 v[176:179], v170 offset:2048
	ds_read_b128 v[180:183], v170 offset:3072
	ds_read_b128 v[184:187], v171
	ds_read_b128 v[188:191], v171 offset:1024
	ds_read_b128 v[192:195], v171 offset:2048
	ds_read_b128 v[196:199], v171 offset:3072
	ds_read_b128 v[200:203], v171 offset:4096
	ds_read_b128 v[204:207], v171 offset:5120
	ds_read_b128 v[208:211], v171 offset:6144
	ds_read_b128 v[212:215], v171 offset:7168
	s_waitcnt vmcnt(8)
	s_waitcnt lgkmcnt(0)
	s_barrier
	s_setprio 1
	s_waitcnt lgkmcnt(0)
	v_mfma_f32_16x16x32_bf16 v[132:135], v[120:123], v[184:187], v[132:135]
	v_mfma_f32_16x16x32_bf16 v[128:131], v[136:139], v[184:187], v[128:131]
	v_mfma_f32_16x16x32_bf16 v[108:111], v[120:123], v[192:195], v[108:111]
	v_mfma_f32_16x16x32_bf16 v[104:107], v[136:139], v[192:195], v[104:107]
	v_mfma_f32_16x16x32_bf16 v[92:95], v[120:123], v[200:203], v[92:95]
	v_mfma_f32_16x16x32_bf16 v[88:91], v[136:139], v[200:203], v[88:91]
	v_mfma_f32_16x16x32_bf16 v[76:79], v[120:123], v[208:211], v[76:79]
	v_mfma_f32_16x16x32_bf16 v[72:75], v[136:139], v[208:211], v[72:75]
	v_mfma_f32_16x16x32_bf16 v[132:135], v[124:127], v[188:191], v[132:135]
	v_mfma_f32_16x16x32_bf16 v[128:131], v[140:143], v[188:191], v[128:131]
	v_mfma_f32_16x16x32_bf16 v[108:111], v[124:127], v[196:199], v[108:111]
	v_mfma_f32_16x16x32_bf16 v[104:107], v[140:143], v[196:199], v[104:107]
	v_mfma_f32_16x16x32_bf16 v[92:95], v[124:127], v[204:207], v[92:95]
	v_mfma_f32_16x16x32_bf16 v[88:91], v[140:143], v[204:207], v[88:91]
	v_mfma_f32_16x16x32_bf16 v[76:79], v[124:127], v[212:215], v[76:79]
	v_mfma_f32_16x16x32_bf16 v[72:75], v[140:143], v[212:215], v[72:75]
	s_setprio 0
	s_setprio 1
	v_mfma_f32_16x16x32_bf16 v[116:119], v[160:163], v[184:187], v[116:119]
	v_mfma_f32_16x16x32_bf16 v[112:115], v[176:179], v[184:187], v[112:115]
	v_mfma_f32_16x16x32_bf16 v[100:103], v[160:163], v[192:195], v[100:103]
	v_mfma_f32_16x16x32_bf16 v[96:99], v[176:179], v[192:195], v[96:99]
	v_mfma_f32_16x16x32_bf16 v[84:87], v[160:163], v[200:203], v[84:87]
	v_mfma_f32_16x16x32_bf16 v[80:83], v[176:179], v[200:203], v[80:83]
	v_mfma_f32_16x16x32_bf16 v[68:71], v[160:163], v[208:211], v[68:71]
	v_mfma_f32_16x16x32_bf16 v[64:67], v[176:179], v[208:211], v[64:67]
	v_mfma_f32_16x16x32_bf16 v[116:119], v[172:175], v[188:191], v[116:119]
	v_mfma_f32_16x16x32_bf16 v[112:115], v[180:183], v[188:191], v[112:115]
	v_mfma_f32_16x16x32_bf16 v[100:103], v[172:175], v[196:199], v[100:103]
	v_mfma_f32_16x16x32_bf16 v[96:99], v[180:183], v[196:199], v[96:99]
	v_mfma_f32_16x16x32_bf16 v[84:87], v[172:175], v[204:207], v[84:87]
	v_mfma_f32_16x16x32_bf16 v[80:83], v[180:183], v[204:207], v[80:83]
	v_mfma_f32_16x16x32_bf16 v[68:71], v[172:175], v[212:215], v[68:71]
	v_mfma_f32_16x16x32_bf16 v[64:67], v[180:183], v[212:215], v[64:67]
	s_setprio 0
	s_barrier
	s_add_i32 s24, s48, s36
	s_mov_b32 m0, s24
	s_nop 0
	global_load_lds_dwordx4 v146, s[28:29]
	s_add_i32 m0, s24, 0x2000
	s_add_u32 s24, s28, 0xb0000
	s_addc_u32 s25, s29, 0
	s_add_i32 s57, s49, s36
	global_load_lds_dwordx4 v150, s[28:29]
	s_mov_b32 m0, s57
	s_nop 0
	global_load_lds_dwordx4 v146, s[24:25]
	s_add_i32 m0, s57, 0x2000
	s_nop 0
	global_load_lds_dwordx4 v150, s[24:25]
	s_mov_b32 m0, s37
	s_nop 0
	global_load_lds_dwordx4 v144, s[30:31]
	s_mov_b32 m0, s38
	s_nop 0
	global_load_lds_dwordx4 v148, s[30:31]
	ds_read_b128 v[184:187], v171 offset:16384
	ds_read_b128 v[188:191], v171 offset:17408
	ds_read_b128 v[192:195], v171 offset:18432
	ds_read_b128 v[196:199], v171 offset:19456
	ds_read_b128 v[200:203], v171 offset:20480
	ds_read_b128 v[204:207], v171 offset:21504
	ds_read_b128 v[208:211], v171 offset:22528
	ds_read_b128 v[212:215], v171 offset:23552
	s_waitcnt vmcnt(8)
	s_waitcnt lgkmcnt(0)
	s_barrier
	s_setprio 1
	s_waitcnt lgkmcnt(0)
	v_mfma_f32_16x16x32_bf16 v[60:63], v[120:123], v[184:187], v[60:63]
	v_mfma_f32_16x16x32_bf16 v[56:59], v[136:139], v[184:187], v[56:59]
	v_mfma_f32_16x16x32_bf16 v[44:47], v[120:123], v[192:195], v[44:47]
	v_mfma_f32_16x16x32_bf16 v[40:43], v[136:139], v[192:195], v[40:43]
	v_mfma_f32_16x16x32_bf16 v[28:31], v[120:123], v[200:203], v[28:31]
	v_mfma_f32_16x16x32_bf16 v[24:27], v[136:139], v[200:203], v[24:27]
	v_mfma_f32_16x16x32_bf16 v[12:15], v[120:123], v[208:211], v[12:15]
	v_mfma_f32_16x16x32_bf16 v[8:11], v[136:139], v[208:211], v[8:11]
	v_mfma_f32_16x16x32_bf16 v[60:63], v[124:127], v[188:191], v[60:63]
	v_mfma_f32_16x16x32_bf16 v[56:59], v[140:143], v[188:191], v[56:59]
	v_mfma_f32_16x16x32_bf16 v[44:47], v[124:127], v[196:199], v[44:47]
	v_mfma_f32_16x16x32_bf16 v[40:43], v[140:143], v[196:199], v[40:43]
	v_mfma_f32_16x16x32_bf16 v[28:31], v[124:127], v[204:207], v[28:31]
	v_mfma_f32_16x16x32_bf16 v[24:27], v[140:143], v[204:207], v[24:27]
	v_mfma_f32_16x16x32_bf16 v[12:15], v[124:127], v[212:215], v[12:15]
	v_mfma_f32_16x16x32_bf16 v[8:11], v[140:143], v[212:215], v[8:11]
	s_setprio 0
	s_setprio 1
	v_mfma_f32_16x16x32_bf16 v[52:55], v[160:163], v[184:187], v[52:55]
	v_mfma_f32_16x16x32_bf16 v[48:51], v[176:179], v[184:187], v[48:51]
	v_mfma_f32_16x16x32_bf16 v[36:39], v[160:163], v[192:195], v[36:39]
	v_mfma_f32_16x16x32_bf16 v[32:35], v[176:179], v[192:195], v[32:35]
	v_mfma_f32_16x16x32_bf16 v[20:23], v[160:163], v[200:203], v[20:23]
	v_mfma_f32_16x16x32_bf16 v[16:19], v[176:179], v[200:203], v[16:19]
	v_mfma_f32_16x16x32_bf16 v[4:7], v[160:163], v[208:211], v[4:7]
	v_mfma_f32_16x16x32_bf16 v[0:3], v[176:179], v[208:211], v[0:3]
	v_mfma_f32_16x16x32_bf16 v[52:55], v[172:175], v[188:191], v[52:55]
	v_mfma_f32_16x16x32_bf16 v[48:51], v[180:183], v[188:191], v[48:51]
	v_mfma_f32_16x16x32_bf16 v[36:39], v[172:175], v[196:199], v[36:39]
	v_mfma_f32_16x16x32_bf16 v[32:35], v[180:183], v[196:199], v[32:35]
	v_mfma_f32_16x16x32_bf16 v[20:23], v[172:175], v[204:207], v[20:23]
	v_mfma_f32_16x16x32_bf16 v[16:19], v[180:183], v[204:207], v[16:19]
	v_mfma_f32_16x16x32_bf16 v[4:7], v[172:175], v[212:215], v[4:7]
	v_mfma_f32_16x16x32_bf16 v[0:3], v[180:183], v[212:215], v[0:3]
	s_setprio 0
	s_barrier
; #define PG8_STAGE(bufoff, gbase, voff) do { _Pragma("unroll") for (int _i = 0; _i < 2; ++_i) \
;         __builtin_amdgcn_global_load_lds((const unsigned*)((const char*)(gbase) + (voff)[_i]), (LAS unsigned*)(lds + (bufoff) + ldsw + _i * 8192), 16, 0, 0); } while (0)
; #define PG8_LDA(dst, b, h) do { _Pragma("unroll") for (int m = 0; m < 4; ++m) _Pragma("unroll") for (int k = 0; k < 2; ++k) dst[m][k] = *(const LAS bf16x8*)(lds + PG8_SA(b, h) + aoff + m * 2048 + k * 1024); } while (0)
; #define PG8_LDB(dst, b, h) do { _Pragma("unroll") for (int n = 0; n < 2; ++n) _Pragma("unroll") for (int k = 0; k < 2; ++k) dst[n][k] = *(const LAS bf16x8*)(lds + PG8_SB(b, h) + boff + n * 2048 + k * 1024); } while (0)
; #define PG8_MMA(ai, bj, At, Bt) do { __builtin_amdgcn_s_setprio(1); _Pragma("unroll") for (int m = 0; m < 4; ++m) _Pragma("unroll") for (int n = 0; n < 2; ++n) _Pragma("unroll") for (int k = 0; k < 2; ++k) \
;         acc[ai][bj][m][n] = __builtin_amdgcn_mfma_f32_16x16x32_bf16(Bt[n][k], At[m][k], acc[ai][bj][m][n], 0, 0, 0); __builtin_amdgcn_s_setprio(0); } while (0)
; #define PG8_WAIT_V(n) asm volatile("s_waitcnt vmcnt(" #n ")" ::: "memory")
; #define PG8_WAIT_L(n) asm volatile("s_waitcnt lgkmcnt(" #n ")" ::: "memory")
; #define PG8_BAR __builtin_amdgcn_s_barrier()
; #define PG8_SCHED __builtin_amdgcn_sched_barrier(0)
; template <class Epi, class Sched, bool ALIGN_EPI, bool SP2>
; __device__ __forceinline__ void gemm_phase(LAS unsigned char* lds, const Gemm g, const Sched& S, const Epi& E) {
;     ...
;             PG8_LDB(B0, 1, 0); PG8_LDB(B1, 1, 1); PG8_SCHED; PG8_LDA(At, 1, 0); PG8_STAGE(PG8_SA(0, 1), a2 + hstep, voffA);
;             PG8_WAIT_V(8); PG8_WAIT_L(0); PG8_BAR; PG8_MMA(0, 0, At, B0); PG8_MMA(0, 1, At, B1); PG8_BAR; PG8_SCHED;
;             PG8_LDA(At, 1, 1); PG8_STAGE(PG8_SB(1, 0), b3, voffB); PG8_STAGE(PG8_SB(1, 1), b3 + hstep, voffB); PG8_STAGE(PG8_SA(1, 0), a3, voffA);
;             PG8_WAIT_V(8); PG8_WAIT_L(0); PG8_BAR; PG8_MMA(1, 0, At, B0); PG8_MMA(1, 1, At, B1); PG8_BAR; PG8_SCHED;
	s_add_i32 s57, 0, 0x18000
	s_add_i32 s58, 0, 0x1c000
	v_add_u32_e32 v140, s57, v167
	v_add_u32_e32 v180, s58, v167
	s_add_u32 s24, s30, 0xb0000
	s_addc_u32 s25, s31, 0
	s_mov_b32 m0, s39
	s_nop 0
	global_load_lds_dwordx4 v144, s[24:25]
	s_mov_b32 m0, s40
	s_nop 0
	global_load_lds_dwordx4 v148, s[24:25]
	ds_read_b128 v[120:123], v140
	ds_read_b128 v[124:127], v140 offset:1024
	ds_read_b128 v[136:139], v140 offset:2048
	ds_read_b128 v[140:143], v140 offset:3072
	ds_read_b128 v[160:163], v180
	ds_read_b128 v[172:175], v180 offset:1024
	ds_read_b128 v[176:179], v180 offset:2048
	ds_read_b128 v[180:183], v180 offset:3072
	ds_read_b128 v[184:187], v171 offset:32768
	ds_read_b128 v[188:191], v171 offset:33792
	ds_read_b128 v[192:195], v171 offset:34816
	ds_read_b128 v[196:199], v171 offset:35840
	ds_read_b128 v[200:203], v171 offset:36864
	ds_read_b128 v[204:207], v171 offset:37888
	ds_read_b128 v[208:211], v171 offset:38912
	ds_read_b128 v[212:215], v171 offset:39936
	s_waitcnt vmcnt(8)
	s_waitcnt lgkmcnt(0)
	s_barrier
	s_setprio 1
	s_waitcnt lgkmcnt(0)
	v_mfma_f32_16x16x32_bf16 v[132:135], v[120:123], v[184:187], v[132:135]
	v_mfma_f32_16x16x32_bf16 v[128:131], v[136:139], v[184:187], v[128:131]
	v_mfma_f32_16x16x32_bf16 v[108:111], v[120:123], v[192:195], v[108:111]
	v_mfma_f32_16x16x32_bf16 v[104:107], v[136:139], v[192:195], v[104:107]
	v_mfma_f32_16x16x32_bf16 v[92:95], v[120:123], v[200:203], v[92:95]
	v_mfma_f32_16x16x32_bf16 v[88:91], v[136:139], v[200:203], v[88:91]
	v_mfma_f32_16x16x32_bf16 v[76:79], v[120:123], v[208:211], v[76:79]
	v_mfma_f32_16x16x32_bf16 v[72:75], v[136:139], v[208:211], v[72:75]
	v_mfma_f32_16x16x32_bf16 v[132:135], v[124:127], v[188:191], v[132:135]
	v_mfma_f32_16x16x32_bf16 v[128:131], v[140:143], v[188:191], v[128:131]
	v_mfma_f32_16x16x32_bf16 v[108:111], v[124:127], v[196:199], v[108:111]
	v_mfma_f32_16x16x32_bf16 v[104:107], v[140:143], v[196:199], v[104:107]
	v_mfma_f32_16x16x32_bf16 v[92:95], v[124:127], v[204:207], v[92:95]
	v_mfma_f32_16x16x32_bf16 v[88:91], v[140:143], v[204:207], v[88:91]
	v_mfma_f32_16x16x32_bf16 v[76:79], v[124:127], v[212:215], v[76:79]
	v_mfma_f32_16x16x32_bf16 v[72:75], v[140:143], v[212:215], v[72:75]
	s_setprio 0
	s_setprio 1
	v_mfma_f32_16x16x32_bf16 v[116:119], v[160:163], v[184:187], v[116:119]
	v_mfma_f32_16x16x32_bf16 v[112:115], v[176:179], v[184:187], v[112:115]
	v_mfma_f32_16x16x32_bf16 v[100:103], v[160:163], v[192:195], v[100:103]
	v_mfma_f32_16x16x32_bf16 v[96:99], v[176:179], v[192:195], v[96:99]
	v_mfma_f32_16x16x32_bf16 v[84:87], v[160:163], v[200:203], v[84:87]
	v_mfma_f32_16x16x32_bf16 v[80:83], v[176:179], v[200:203], v[80:83]
	v_mfma_f32_16x16x32_bf16 v[68:71], v[160:163], v[208:211], v[68:71]
	v_mfma_f32_16x16x32_bf16 v[64:67], v[176:179], v[208:211], v[64:67]
	v_mfma_f32_16x16x32_bf16 v[116:119], v[172:175], v[188:191], v[116:119]
	v_mfma_f32_16x16x32_bf16 v[112:115], v[180:183], v[188:191], v[112:115]
	v_mfma_f32_16x16x32_bf16 v[100:103], v[172:175], v[196:199], v[100:103]
	v_mfma_f32_16x16x32_bf16 v[96:99], v[180:183], v[196:199], v[96:99]
	v_mfma_f32_16x16x32_bf16 v[84:87], v[172:175], v[204:207], v[84:87]
	v_mfma_f32_16x16x32_bf16 v[80:83], v[180:183], v[204:207], v[80:83]
	v_mfma_f32_16x16x32_bf16 v[68:71], v[172:175], v[212:215], v[68:71]
	v_mfma_f32_16x16x32_bf16 v[64:67], v[180:183], v[212:215], v[64:67]
	s_setprio 0
	s_barrier
	s_add_u32 s100, s24, 0xfff50080
	s_addc_u32 s101, s25, -1
	s_add_u32 s98, s28, 0x80
	s_addc_u32 s99, s29, 0
	s_add_i32 s24, s57, s36
	s_mov_b32 m0, s24
	s_nop 0
	global_load_lds_dwordx4 v146, s[98:99]
	s_add_i32 m0, s24, 0x2000
	s_add_u32 s24, s28, 0xb0080
	s_addc_u32 s25, s29, 0
	s_add_i32 s28, s58, s36
	global_load_lds_dwordx4 v150, s[98:99]
	s_mov_b32 m0, s28
	s_nop 0
	global_load_lds_dwordx4 v146, s[24:25]
	s_add_i32 m0, s28, 0x2000
	s_nop 0
	global_load_lds_dwordx4 v150, s[24:25]
	s_mov_b32 m0, s45
	s_nop 0
	global_load_lds_dwordx4 v144, s[100:101]
	s_mov_b32 m0, s46
	s_nop 0
	global_load_lds_dwordx4 v148, s[100:101]
	ds_read_b128 v[184:187], v171 offset:49152
	ds_read_b128 v[188:191], v171 offset:50176
	ds_read_b128 v[192:195], v171 offset:51200
	ds_read_b128 v[196:199], v171 offset:52224
	ds_read_b128 v[200:203], v171 offset:53248
	ds_read_b128 v[204:207], v171 offset:54272
	ds_read_b128 v[208:211], v171 offset:55296
	ds_read_b128 v[212:215], v171 offset:56320
	s_waitcnt vmcnt(8)
	s_waitcnt lgkmcnt(0)
	s_barrier
	s_setprio 1
	s_waitcnt lgkmcnt(0)
	v_mfma_f32_16x16x32_bf16 v[60:63], v[120:123], v[184:187], v[60:63]
	v_mfma_f32_16x16x32_bf16 v[56:59], v[136:139], v[184:187], v[56:59]
	v_mfma_f32_16x16x32_bf16 v[44:47], v[120:123], v[192:195], v[44:47]
	v_mfma_f32_16x16x32_bf16 v[40:43], v[136:139], v[192:195], v[40:43]
	v_mfma_f32_16x16x32_bf16 v[28:31], v[120:123], v[200:203], v[28:31]
	v_mfma_f32_16x16x32_bf16 v[24:27], v[136:139], v[200:203], v[24:27]
	v_mfma_f32_16x16x32_bf16 v[12:15], v[120:123], v[208:211], v[12:15]
	v_mfma_f32_16x16x32_bf16 v[8:11], v[136:139], v[208:211], v[8:11]
	v_mfma_f32_16x16x32_bf16 v[60:63], v[124:127], v[188:191], v[60:63]
	v_mfma_f32_16x16x32_bf16 v[56:59], v[140:143], v[188:191], v[56:59]
	v_mfma_f32_16x16x32_bf16 v[44:47], v[124:127], v[196:199], v[44:47]
	v_mfma_f32_16x16x32_bf16 v[40:43], v[140:143], v[196:199], v[40:43]
	v_mfma_f32_16x16x32_bf16 v[28:31], v[124:127], v[204:207], v[28:31]
	v_mfma_f32_16x16x32_bf16 v[24:27], v[140:143], v[204:207], v[24:27]
	v_mfma_f32_16x16x32_bf16 v[12:15], v[124:127], v[212:215], v[12:15]
	v_mfma_f32_16x16x32_bf16 v[8:11], v[140:143], v[212:215], v[8:11]
	s_setprio 0
	s_setprio 1
	v_mfma_f32_16x16x32_bf16 v[52:55], v[160:163], v[184:187], v[52:55]
	v_mfma_f32_16x16x32_bf16 v[48:51], v[176:179], v[184:187], v[48:51]
	v_mfma_f32_16x16x32_bf16 v[36:39], v[160:163], v[192:195], v[36:39]
	v_mfma_f32_16x16x32_bf16 v[32:35], v[176:179], v[192:195], v[32:35]
	v_mfma_f32_16x16x32_bf16 v[20:23], v[160:163], v[200:203], v[20:23]
	v_mfma_f32_16x16x32_bf16 v[16:19], v[176:179], v[200:203], v[16:19]
	v_mfma_f32_16x16x32_bf16 v[4:7], v[160:163], v[208:211], v[4:7]
	v_mfma_f32_16x16x32_bf16 v[0:3], v[176:179], v[208:211], v[0:3]
	v_mfma_f32_16x16x32_bf16 v[52:55], v[172:175], v[188:191], v[52:55]
	v_mfma_f32_16x16x32_bf16 v[48:51], v[180:183], v[188:191], v[48:51]
	v_mfma_f32_16x16x32_bf16 v[36:39], v[172:175], v[196:199], v[36:39]
	v_mfma_f32_16x16x32_bf16 v[32:35], v[180:183], v[196:199], v[32:35]
	v_mfma_f32_16x16x32_bf16 v[20:23], v[172:175], v[204:207], v[20:23]
	v_mfma_f32_16x16x32_bf16 v[16:19], v[180:183], v[204:207], v[16:19]
	v_mfma_f32_16x16x32_bf16 v[4:7], v[172:175], v[212:215], v[4:7]
	v_mfma_f32_16x16x32_bf16 v[0:3], v[180:183], v[212:215], v[0:3]
	s_setprio 0
	s_barrier
	s_add_i32 s56, s56, 2
	s_add_u32 s54, s54, 0x100
	s_addc_u32 s55, s55, 0
	s_cmp_gt_u32 s56, 41
	s_mov_b64 s[24:25], s[26:27]
	s_cbranch_scc0 .LBB0_766
	s_and_b64 vcc, exec, s[12:13]
	s_cbranch_vccz .LBB0_769
	s_barrier
